# a+b plus: nt (streaming) policy on the P1 epilogue bf16 stores (do not displace staged operand tiles in L2)
# speedup vs baseline: 1.0056x; 1.0025x over previous
; __device__ __forceinline__ unsigned cvt_pk_bf16(float lo, float hi) { unsigned r; asm volatile("v_cvt_pk_bf16_f32 %0, %1, %2" : "=v"(r) : "v"(lo), "v"(hi)); return r; }
; __device__ __forceinline__ f32x2p gelu_tanh_pk(f32x2p v) { const f32x2p t = v * (v * v * -0.10294324f + -2.3022082f); return v * rcp1p_exp2_pk(t); }
; __device__ __forceinline__ f32x2p sigmoid_pk(f32x2p z) { return rcp1p_exp2_pk(z * -1.4426950409f); }
;     __device__ __forceinline__ void operator()(const f32x4 (&acc)[2][2][4][2], const Unit& u, int wr, int wc, int fr, int fq) const {
;     ...
;             for (int m = 0; m < 4; ++m) { const int row = row0 + ai * HALF + m * 16; bf16_t* rowp = base + (size_t)row * ldc + col0; float s = 0.f, q = 0.f;
; #pragma unroll
;                 for (int bj = 0; bj < 2; ++bj) { f32x4 v0 = acc[ai][bj][m][0], v1 = acc[ai][bj][m][1];
;                     if (act == 1) { const f32x2p a0 = gelu_tanh_pk((f32x2p){v0[0], v0[1]}), a1 = gelu_tanh_pk((f32x2p){v0[2], v0[3]}), a2 = gelu_tanh_pk((f32x2p){v1[0], v1[1]}), a3 = gelu_tanh_pk((f32x2p){v1[2], v1[3]});
;                         v0 = (f32x4){a0.x, a0.y, a1.x, a1.y}; v1 = (f32x4){a2.x, a2.y, a3.x, a3.y}; }
;                     else if (act == 2) { const f32x2p a0 = sigmoid_pk((f32x2p){v0[0], v0[1]}), a1 = sigmoid_pk((f32x2p){v0[2], v0[3]}), a2 = sigmoid_pk((f32x2p){v1[0], v1[1]}), a3 = sigmoid_pk((f32x2p){v1[2], v1[3]});
;                         v0 = (f32x4){a0.x, a0.y, a1.x, a1.y}; v1 = (f32x4){a2.x, a2.y, a3.x, a3.y}; }
;                     if (st) {
; #pragma unroll
;                         for (int j = 0; j < 4; ++j) { s += v0[j] + v1[j]; q += v0[j] * v0[j] + v1[j] * v1[j]; } }
;                     u32x4 w; w.x = cvt_pk_bf16(v0[0], v0[1]); w.y = cvt_pk_bf16(v0[2], v0[3]); w.z = cvt_pk_bf16(v1[0], v1[1]); w.w = cvt_pk_bf16(v1[2], v1[3]);
;                     *(u32x4*)(rowp + bj * HALF) = w; }
.LBB0_360:
	v_lshl_add_u32 v124, s10, 8, v147
	v_add_u32_e32 v122, s11, v149
	v_ashrrev_i32_e32 v125, 31, v124
	v_ashrrev_i32_e32 v123, 31, v122
	v_mul_lo_u32 v135, s86, v125
	v_mul_lo_u32 v154, s87, v124
	v_mad_u64_u32 v[128:129], s[10:11], s86, v124, 0
	v_lshl_add_u64 v[122:123], v[122:123], 1, s[14:15]
	v_add3_u32 v129, v129, v135, v154
	v_cndmask_b32_e64 v135, 0, 1, s[2:3]
	v_lshl_add_u64 v[128:129], v[128:129], 1, v[122:123]
	v_cmp_ne_u32_e64 s[12:13], 1, v135
	s_andn2_b64 vcc, exec, s[2:3]
	s_mov_b64 s[2:3], -1
	v_cvt_pk_bf16_f32 v154, v138, v139
	v_cvt_pk_bf16_f32 v155, v136, v137
	v_cvt_pk_bf16_f32 v156, v142, v143
	v_cvt_pk_bf16_f32 v157, v140, v141
	global_store_dwordx4 v[128:129], v[154:157], off nt
	s_cbranch_vccnz .LBB0_377
	s_and_b64 vcc, exec, s[8:9]
	v_mov_b32_e32 v137, v121
	v_mov_b32_e32 v136, v120
	v_mov_b32_e32 v139, v119
	v_mov_b32_e32 v138, v118
	v_mov_b32_e32 v141, v117
	v_mov_b32_e32 v140, v116
	v_mov_b32_e32 v143, v115
	v_mov_b32_e32 v142, v114
	s_cbranch_vccnz .LBB0_363
	v_pk_mul_f32 v[136:137], v[118:119], s[60:61] op_sel_hi:[1,0]
	v_pk_mul_f32 v[138:139], v[120:121], s[60:61] op_sel_hi:[1,0]
	v_exp_f32_e32 v136, v136
	v_exp_f32_e32 v137, v137
	v_exp_f32_e32 v140, v138
	v_exp_f32_e32 v141, v139
	v_pk_mul_f32 v[142:143], v[116:117], s[60:61] op_sel_hi:[1,0]
	v_pk_add_f32 v[136:137], v[136:137], 1.0 op_sel_hi:[1,0]
	v_exp_f32_e32 v154, v142
	v_rcp_f32_e32 v138, v136
	v_rcp_f32_e32 v139, v137
	v_pk_add_f32 v[136:137], v[140:141], 1.0 op_sel_hi:[1,0]
	v_pk_mul_f32 v[140:141], v[114:115], s[60:61] op_sel_hi:[1,0]
	v_exp_f32_e32 v155, v143
	v_exp_f32_e32 v140, v140
	v_exp_f32_e32 v141, v141
	v_rcp_f32_e32 v136, v136
	v_rcp_f32_e32 v137, v137
	v_pk_add_f32 v[140:141], v[140:141], 1.0 op_sel_hi:[1,0]
	s_nop 0
	v_rcp_f32_e32 v142, v140
	v_rcp_f32_e32 v143, v141
	v_pk_add_f32 v[140:141], v[154:155], 1.0 op_sel_hi:[1,0]
	s_nop 0
	v_rcp_f32_e32 v140, v140
	v_rcp_f32_e32 v141, v141

; __device__ __forceinline__ unsigned cvt_pk_bf16(float lo, float hi) { unsigned r; asm volatile("v_cvt_pk_bf16_f32 %0, %1, %2" : "=v"(r) : "v"(lo), "v"(hi)); return r; }
;     __device__ __forceinline__ void operator()(const f32x4 (&acc)[2][2][4][2], const Unit& u, int wr, int wc, int fr, int fq) const {
;     ...
;                     u32x4 w; w.x = cvt_pk_bf16(v0[0], v0[1]); w.y = cvt_pk_bf16(v0[2], v0[3]); w.z = cvt_pk_bf16(v1[0], v1[1]); w.w = cvt_pk_bf16(v1[2], v1[3]);
;                     *(u32x4*)(rowp + bj * HALF) = w; }
;                 if (st) { s += __shfl_xor(s, 16); s += __shfl_xor(s, 32); q += __shfl_xor(q, 16); q += __shfl_xor(q, 32);
;                     if (fq == 0) { unsafeAtomicAdd(vsum + row, s); unsafeAtomicAdd(vsq + row, q); } } }
.LBB0_366:
	s_and_b64 vcc, exec, s[10:11]
	v_cvt_pk_bf16_f32 v114, v138, v139
	v_cvt_pk_bf16_f32 v115, v136, v137
	v_cvt_pk_bf16_f32 v116, v142, v143
	v_cvt_pk_bf16_f32 v117, v140, v141
	global_store_dwordx4 v[128:129], v[114:117], off offset:256 nt
	s_cbranch_vccnz .LBB0_370
	s_nop 0
	v_and_b32_e32 v115, 64, v153
	v_xor_b32_e32 v114, 16, v153
	v_add_u32_e32 v115, 64, v115
	v_cmp_lt_i32_e32 vcc, v114, v115
	v_xor_b32_e32 v117, 32, v153
	s_nop 0
	v_cndmask_b32_e32 v114, v153, v114, vcc
	v_lshlrev_b32_e32 v114, 2, v114
	ds_bpermute_b32 v116, v114, v127
	ds_bpermute_b32 v118, v114, v126
	v_cmp_lt_i32_e32 vcc, v117, v115
	s_waitcnt lgkmcnt(0)
	v_add_f32_e32 v114, v127, v116
	v_cndmask_b32_e32 v115, v153, v117, vcc
	v_lshlrev_b32_e32 v117, 2, v115
	v_add_f32_e32 v116, v126, v118
	ds_bpermute_b32 v115, v117, v114
	ds_bpermute_b32 v117, v117, v116
	s_and_saveexec_b64 s[2:3], s[4:5]
	s_cbranch_execz .LBB0_369
	v_lshlrev_b64 v[118:119], 2, v[124:125]
	v_lshl_add_u64 v[120:121], s[56:57], 0, v[118:119]
	v_lshl_add_u64 v[118:119], s[54:55], 0, v[118:119]
	s_waitcnt lgkmcnt(0)
	v_add_f32_e32 v114, v114, v115
	v_add_f32_e32 v115, v116, v117
	global_atomic_add_f32 v[118:119], v114, off
	global_atomic_add_f32 v[120:121], v115, off

; __device__ __forceinline__ unsigned cvt_pk_bf16(float lo, float hi) { unsigned r; asm volatile("v_cvt_pk_bf16_f32 %0, %1, %2" : "=v"(r) : "v"(lo), "v"(hi)); return r; }
; __device__ __forceinline__ f32x2p gelu_tanh_pk(f32x2p v) { const f32x2p t = v * (v * v * -0.10294324f + -2.3022082f); return v * rcp1p_exp2_pk(t); }
; __device__ __forceinline__ f32x2p sigmoid_pk(f32x2p z) { return rcp1p_exp2_pk(z * -1.4426950409f); }
;     __device__ __forceinline__ void operator()(const f32x4 (&acc)[2][2][4][2], const Unit& u, int wr, int wc, int fr, int fq) const {
;     ...
;             for (int m = 0; m < 4; ++m) { const int row = row0 + ai * HALF + m * 16; bf16_t* rowp = base + (size_t)row * ldc + col0; float s = 0.f, q = 0.f;
; #pragma unroll
;                 for (int bj = 0; bj < 2; ++bj) { f32x4 v0 = acc[ai][bj][m][0], v1 = acc[ai][bj][m][1];
;                     if (act == 1) { const f32x2p a0 = gelu_tanh_pk((f32x2p){v0[0], v0[1]}), a1 = gelu_tanh_pk((f32x2p){v0[2], v0[3]}), a2 = gelu_tanh_pk((f32x2p){v1[0], v1[1]}), a3 = gelu_tanh_pk((f32x2p){v1[2], v1[3]});
;                         v0 = (f32x4){a0.x, a0.y, a1.x, a1.y}; v1 = (f32x4){a2.x, a2.y, a3.x, a3.y}; }
;                     else if (act == 2) { const f32x2p a0 = sigmoid_pk((f32x2p){v0[0], v0[1]}), a1 = sigmoid_pk((f32x2p){v0[2], v0[3]}), a2 = sigmoid_pk((f32x2p){v1[0], v1[1]}), a3 = sigmoid_pk((f32x2p){v1[2], v1[3]});
;                         v0 = (f32x4){a0.x, a0.y, a1.x, a1.y}; v1 = (f32x4){a2.x, a2.y, a3.x, a3.y}; }
;                     if (st) {
; #pragma unroll
;                         for (int j = 0; j < 4; ++j) { s += v0[j] + v1[j]; q += v0[j] * v0[j] + v1[j] * v1[j]; } }
;                     u32x4 w; w.x = cvt_pk_bf16(v0[0], v0[1]); w.y = cvt_pk_bf16(v0[2], v0[3]); w.z = cvt_pk_bf16(v1[0], v1[1]); w.w = cvt_pk_bf16(v1[2], v1[3]);
;                     *(u32x4*)(rowp + bj * HALF) = w; }
.LBB0_383:
	v_or_b32_e32 v106, 16, v124
	v_ashrrev_i32_e32 v107, 31, v106
	v_mul_lo_u32 v112, s86, v107
	v_mul_lo_u32 v113, s87, v106
	v_mad_u64_u32 v[110:111], s[2:3], s86, v106, 0
	v_add3_u32 v111, v111, v112, v113
	v_lshl_add_u64 v[110:111], v[110:111], 1, v[122:123]
	s_waitcnt lgkmcnt(0)
	v_cvt_pk_bf16_f32 v112, v116, v117
	v_cvt_pk_bf16_f32 v113, v114, v115
	v_cvt_pk_bf16_f32 v114, v120, v121
	v_cvt_pk_bf16_f32 v115, v118, v119
	s_and_b64 vcc, exec, s[12:13]
	s_mov_b64 s[2:3], -1
	global_store_dwordx4 v[110:111], v[112:115], off nt
	s_cbranch_vccnz .LBB0_400
	s_and_b64 vcc, exec, s[8:9]
	v_mov_b32_e32 v113, v105
	v_mov_b32_e32 v112, v104
	v_mov_b32_e32 v115, v103
	v_mov_b32_e32 v114, v102
	v_mov_b32_e32 v117, v101
	v_mov_b32_e32 v116, v100
	v_mov_b32_e32 v119, v99
	v_mov_b32_e32 v118, v98
	s_cbranch_vccnz .LBB0_386
	v_pk_mul_f32 v[112:113], v[102:103], s[60:61] op_sel_hi:[1,0]
	v_pk_mul_f32 v[114:115], v[104:105], s[60:61] op_sel_hi:[1,0]
	v_exp_f32_e32 v112, v112
	v_exp_f32_e32 v113, v113
	v_exp_f32_e32 v116, v114
	v_exp_f32_e32 v117, v115
	v_pk_mul_f32 v[118:119], v[100:101], s[60:61] op_sel_hi:[1,0]
	v_pk_add_f32 v[112:113], v[112:113], 1.0 op_sel_hi:[1,0]
	v_exp_f32_e32 v120, v118
	v_rcp_f32_e32 v114, v112
	v_rcp_f32_e32 v115, v113
	v_pk_add_f32 v[112:113], v[116:117], 1.0 op_sel_hi:[1,0]
	v_pk_mul_f32 v[116:117], v[98:99], s[60:61] op_sel_hi:[1,0]
	v_exp_f32_e32 v121, v119
	v_exp_f32_e32 v116, v116
	v_exp_f32_e32 v117, v117
	v_rcp_f32_e32 v112, v112
	v_rcp_f32_e32 v113, v113
	v_pk_add_f32 v[116:117], v[116:117], 1.0 op_sel_hi:[1,0]
	s_nop 0
	v_rcp_f32_e32 v118, v116
	v_rcp_f32_e32 v119, v117
	v_pk_add_f32 v[116:117], v[120:121], 1.0 op_sel_hi:[1,0]
	s_nop 0
	v_rcp_f32_e32 v116, v116
	v_rcp_f32_e32 v117, v117

; __device__ __forceinline__ unsigned cvt_pk_bf16(float lo, float hi) { unsigned r; asm volatile("v_cvt_pk_bf16_f32 %0, %1, %2" : "=v"(r) : "v"(lo), "v"(hi)); return r; }
;     __device__ __forceinline__ void operator()(const f32x4 (&acc)[2][2][4][2], const Unit& u, int wr, int wc, int fr, int fq) const {
;     ...
;                     u32x4 w; w.x = cvt_pk_bf16(v0[0], v0[1]); w.y = cvt_pk_bf16(v0[2], v0[3]); w.z = cvt_pk_bf16(v1[0], v1[1]); w.w = cvt_pk_bf16(v1[2], v1[3]);
;                     *(u32x4*)(rowp + bj * HALF) = w; }
;                 if (st) { s += __shfl_xor(s, 16); s += __shfl_xor(s, 32); q += __shfl_xor(q, 16); q += __shfl_xor(q, 32);
;                     if (fq == 0) { unsafeAtomicAdd(vsum + row, s); unsafeAtomicAdd(vsq + row, q); } } }
.LBB0_389:
	s_and_b64 vcc, exec, s[10:11]
	v_cvt_pk_bf16_f32 v98, v114, v115
	v_cvt_pk_bf16_f32 v99, v112, v113
	v_cvt_pk_bf16_f32 v100, v118, v119
	v_cvt_pk_bf16_f32 v101, v116, v117
	global_store_dwordx4 v[110:111], v[98:101], off offset:256 nt
	s_cbranch_vccnz .LBB0_393
	s_nop 0
	v_and_b32_e32 v99, 64, v153
	v_xor_b32_e32 v98, 16, v153
	v_add_u32_e32 v99, 64, v99
	v_cmp_lt_i32_e32 vcc, v98, v99
	v_xor_b32_e32 v101, 32, v153
	s_nop 0
	v_cndmask_b32_e32 v98, v153, v98, vcc
	v_lshlrev_b32_e32 v98, 2, v98
	ds_bpermute_b32 v100, v98, v109
	ds_bpermute_b32 v102, v98, v108
	v_cmp_lt_i32_e32 vcc, v101, v99
	s_waitcnt lgkmcnt(0)
	v_add_f32_e32 v98, v109, v100
	v_cndmask_b32_e32 v99, v153, v101, vcc
	v_lshlrev_b32_e32 v101, 2, v99
	v_add_f32_e32 v100, v108, v102
	ds_bpermute_b32 v99, v101, v98
	ds_bpermute_b32 v101, v101, v100
	s_and_saveexec_b64 s[2:3], s[4:5]
	s_cbranch_execz .LBB0_392
	v_lshlrev_b64 v[102:103], 2, v[106:107]
	v_lshl_add_u64 v[104:105], s[56:57], 0, v[102:103]
	v_lshl_add_u64 v[102:103], s[54:55], 0, v[102:103]
	s_waitcnt lgkmcnt(0)
	v_add_f32_e32 v98, v98, v99
	v_add_f32_e32 v99, v100, v101
	global_atomic_add_f32 v[102:103], v98, off
	global_atomic_add_f32 v[104:105], v99, off

; __device__ __forceinline__ unsigned cvt_pk_bf16(float lo, float hi) { unsigned r; asm volatile("v_cvt_pk_bf16_f32 %0, %1, %2" : "=v"(r) : "v"(lo), "v"(hi)); return r; }
; __device__ __forceinline__ f32x2p gelu_tanh_pk(f32x2p v) { const f32x2p t = v * (v * v * -0.10294324f + -2.3022082f); return v * rcp1p_exp2_pk(t); }
; __device__ __forceinline__ f32x2p sigmoid_pk(f32x2p z) { return rcp1p_exp2_pk(z * -1.4426950409f); }
;     __device__ __forceinline__ void operator()(const f32x4 (&acc)[2][2][4][2], const Unit& u, int wr, int wc, int fr, int fq) const {
;     ...
;             for (int m = 0; m < 4; ++m) { const int row = row0 + ai * HALF + m * 16; bf16_t* rowp = base + (size_t)row * ldc + col0; float s = 0.f, q = 0.f;
; #pragma unroll
;                 for (int bj = 0; bj < 2; ++bj) { f32x4 v0 = acc[ai][bj][m][0], v1 = acc[ai][bj][m][1];
;                     if (act == 1) { const f32x2p a0 = gelu_tanh_pk((f32x2p){v0[0], v0[1]}), a1 = gelu_tanh_pk((f32x2p){v0[2], v0[3]}), a2 = gelu_tanh_pk((f32x2p){v1[0], v1[1]}), a3 = gelu_tanh_pk((f32x2p){v1[2], v1[3]});
;                         v0 = (f32x4){a0.x, a0.y, a1.x, a1.y}; v1 = (f32x4){a2.x, a2.y, a3.x, a3.y}; }
;                     else if (act == 2) { const f32x2p a0 = sigmoid_pk((f32x2p){v0[0], v0[1]}), a1 = sigmoid_pk((f32x2p){v0[2], v0[3]}), a2 = sigmoid_pk((f32x2p){v1[0], v1[1]}), a3 = sigmoid_pk((f32x2p){v1[2], v1[3]});
;                         v0 = (f32x4){a0.x, a0.y, a1.x, a1.y}; v1 = (f32x4){a2.x, a2.y, a3.x, a3.y}; }
;                     if (st) {
; #pragma unroll
;                         for (int j = 0; j < 4; ++j) { s += v0[j] + v1[j]; q += v0[j] * v0[j] + v1[j] * v1[j]; } }
;                     u32x4 w; w.x = cvt_pk_bf16(v0[0], v0[1]); w.y = cvt_pk_bf16(v0[2], v0[3]); w.z = cvt_pk_bf16(v1[0], v1[1]); w.w = cvt_pk_bf16(v1[2], v1[3]);
;                     *(u32x4*)(rowp + bj * HALF) = w; }
.LBB0_406:
	v_or_b32_e32 v90, 32, v124
	v_ashrrev_i32_e32 v91, 31, v90
	v_mul_lo_u32 v96, s86, v91
	v_mul_lo_u32 v97, s87, v90
	v_mad_u64_u32 v[94:95], s[2:3], s86, v90, 0
	v_add3_u32 v95, v95, v96, v97
	v_lshl_add_u64 v[94:95], v[94:95], 1, v[122:123]
	s_waitcnt lgkmcnt(0)
	v_cvt_pk_bf16_f32 v96, v100, v101
	v_cvt_pk_bf16_f32 v97, v98, v99
	v_cvt_pk_bf16_f32 v98, v104, v105
	v_cvt_pk_bf16_f32 v99, v102, v103
	s_and_b64 vcc, exec, s[12:13]
	s_mov_b64 s[2:3], -1
	global_store_dwordx4 v[94:95], v[96:99], off nt
	s_cbranch_vccnz .LBB0_423
	s_and_b64 vcc, exec, s[8:9]
	v_mov_b32_e32 v97, v89
	v_mov_b32_e32 v96, v88
	v_mov_b32_e32 v99, v87
	v_mov_b32_e32 v98, v86
	v_mov_b32_e32 v101, v85
	v_mov_b32_e32 v100, v84
	v_mov_b32_e32 v103, v83
	v_mov_b32_e32 v102, v82
	s_cbranch_vccnz .LBB0_409
	v_pk_mul_f32 v[96:97], v[86:87], s[60:61] op_sel_hi:[1,0]
	v_pk_mul_f32 v[98:99], v[88:89], s[60:61] op_sel_hi:[1,0]
	v_exp_f32_e32 v96, v96
	v_exp_f32_e32 v97, v97
	v_exp_f32_e32 v100, v98
	v_exp_f32_e32 v101, v99
	v_pk_mul_f32 v[102:103], v[84:85], s[60:61] op_sel_hi:[1,0]
	v_pk_add_f32 v[96:97], v[96:97], 1.0 op_sel_hi:[1,0]
	v_exp_f32_e32 v104, v102
	v_rcp_f32_e32 v98, v96
	v_rcp_f32_e32 v99, v97
	v_pk_add_f32 v[96:97], v[100:101], 1.0 op_sel_hi:[1,0]
	v_pk_mul_f32 v[100:101], v[82:83], s[60:61] op_sel_hi:[1,0]
	v_exp_f32_e32 v105, v103
	v_exp_f32_e32 v100, v100
	v_exp_f32_e32 v101, v101
	v_rcp_f32_e32 v96, v96
	v_rcp_f32_e32 v97, v97
	v_pk_add_f32 v[100:101], v[100:101], 1.0 op_sel_hi:[1,0]
	s_nop 0
	v_rcp_f32_e32 v102, v100
	v_rcp_f32_e32 v103, v101
	v_pk_add_f32 v[100:101], v[104:105], 1.0 op_sel_hi:[1,0]
	s_nop 0
	v_rcp_f32_e32 v100, v100
	v_rcp_f32_e32 v101, v101

; __device__ __forceinline__ unsigned cvt_pk_bf16(float lo, float hi) { unsigned r; asm volatile("v_cvt_pk_bf16_f32 %0, %1, %2" : "=v"(r) : "v"(lo), "v"(hi)); return r; }
;     __device__ __forceinline__ void operator()(const f32x4 (&acc)[2][2][4][2], const Unit& u, int wr, int wc, int fr, int fq) const {
;     ...
;                     u32x4 w; w.x = cvt_pk_bf16(v0[0], v0[1]); w.y = cvt_pk_bf16(v0[2], v0[3]); w.z = cvt_pk_bf16(v1[0], v1[1]); w.w = cvt_pk_bf16(v1[2], v1[3]);
;                     *(u32x4*)(rowp + bj * HALF) = w; }
;                 if (st) { s += __shfl_xor(s, 16); s += __shfl_xor(s, 32); q += __shfl_xor(q, 16); q += __shfl_xor(q, 32);
;                     if (fq == 0) { unsafeAtomicAdd(vsum + row, s); unsafeAtomicAdd(vsq + row, q); } } }
.LBB0_412:
	s_and_b64 vcc, exec, s[10:11]
	v_cvt_pk_bf16_f32 v82, v98, v99
	v_cvt_pk_bf16_f32 v83, v96, v97
	v_cvt_pk_bf16_f32 v84, v102, v103
	v_cvt_pk_bf16_f32 v85, v100, v101
	global_store_dwordx4 v[94:95], v[82:85], off offset:256 nt
	s_cbranch_vccnz .LBB0_416
	s_nop 0
	v_and_b32_e32 v83, 64, v153
	v_xor_b32_e32 v82, 16, v153
	v_add_u32_e32 v83, 64, v83
	v_cmp_lt_i32_e32 vcc, v82, v83
	v_xor_b32_e32 v85, 32, v153
	s_nop 0
	v_cndmask_b32_e32 v82, v153, v82, vcc
	v_lshlrev_b32_e32 v82, 2, v82
	ds_bpermute_b32 v84, v82, v93
	ds_bpermute_b32 v86, v82, v92
	v_cmp_lt_i32_e32 vcc, v85, v83
	s_waitcnt lgkmcnt(0)
	v_add_f32_e32 v82, v93, v84
	v_cndmask_b32_e32 v83, v153, v85, vcc
	v_lshlrev_b32_e32 v85, 2, v83
	v_add_f32_e32 v84, v92, v86
	ds_bpermute_b32 v83, v85, v82
	ds_bpermute_b32 v85, v85, v84
	s_and_saveexec_b64 s[2:3], s[4:5]
	s_cbranch_execz .LBB0_415
	v_lshlrev_b64 v[86:87], 2, v[90:91]
	v_lshl_add_u64 v[88:89], s[56:57], 0, v[86:87]
	v_lshl_add_u64 v[86:87], s[54:55], 0, v[86:87]
	s_waitcnt lgkmcnt(0)
	v_add_f32_e32 v82, v82, v83
	v_add_f32_e32 v83, v84, v85
	global_atomic_add_f32 v[86:87], v82, off
	global_atomic_add_f32 v[88:89], v83, off

; __device__ __forceinline__ unsigned cvt_pk_bf16(float lo, float hi) { unsigned r; asm volatile("v_cvt_pk_bf16_f32 %0, %1, %2" : "=v"(r) : "v"(lo), "v"(hi)); return r; }
; __device__ __forceinline__ f32x2p gelu_tanh_pk(f32x2p v) { const f32x2p t = v * (v * v * -0.10294324f + -2.3022082f); return v * rcp1p_exp2_pk(t); }
; __device__ __forceinline__ f32x2p sigmoid_pk(f32x2p z) { return rcp1p_exp2_pk(z * -1.4426950409f); }
;     __device__ __forceinline__ void operator()(const f32x4 (&acc)[2][2][4][2], const Unit& u, int wr, int wc, int fr, int fq) const {
;     ...
;             for (int m = 0; m < 4; ++m) { const int row = row0 + ai * HALF + m * 16; bf16_t* rowp = base + (size_t)row * ldc + col0; float s = 0.f, q = 0.f;
; #pragma unroll
;                 for (int bj = 0; bj < 2; ++bj) { f32x4 v0 = acc[ai][bj][m][0], v1 = acc[ai][bj][m][1];
;                     if (act == 1) { const f32x2p a0 = gelu_tanh_pk((f32x2p){v0[0], v0[1]}), a1 = gelu_tanh_pk((f32x2p){v0[2], v0[3]}), a2 = gelu_tanh_pk((f32x2p){v1[0], v1[1]}), a3 = gelu_tanh_pk((f32x2p){v1[2], v1[3]});
;                         v0 = (f32x4){a0.x, a0.y, a1.x, a1.y}; v1 = (f32x4){a2.x, a2.y, a3.x, a3.y}; }
;                     else if (act == 2) { const f32x2p a0 = sigmoid_pk((f32x2p){v0[0], v0[1]}), a1 = sigmoid_pk((f32x2p){v0[2], v0[3]}), a2 = sigmoid_pk((f32x2p){v1[0], v1[1]}), a3 = sigmoid_pk((f32x2p){v1[2], v1[3]});
;                         v0 = (f32x4){a0.x, a0.y, a1.x, a1.y}; v1 = (f32x4){a2.x, a2.y, a3.x, a3.y}; }
;                     if (st) {
; #pragma unroll
;                         for (int j = 0; j < 4; ++j) { s += v0[j] + v1[j]; q += v0[j] * v0[j] + v1[j] * v1[j]; } }
;                     u32x4 w; w.x = cvt_pk_bf16(v0[0], v0[1]); w.y = cvt_pk_bf16(v0[2], v0[3]); w.z = cvt_pk_bf16(v1[0], v1[1]); w.w = cvt_pk_bf16(v1[2], v1[3]);
;                     *(u32x4*)(rowp + bj * HALF) = w; }
.LBB0_429:
	v_or_b32_e32 v74, 48, v124
	v_ashrrev_i32_e32 v75, 31, v74
	v_mul_lo_u32 v80, s86, v75
	v_mul_lo_u32 v81, s87, v74
	v_mad_u64_u32 v[78:79], s[2:3], s86, v74, 0
	v_add3_u32 v79, v79, v80, v81
	v_lshl_add_u64 v[78:79], v[78:79], 1, v[122:123]
	s_waitcnt lgkmcnt(0)
	v_cvt_pk_bf16_f32 v80, v84, v85
	v_cvt_pk_bf16_f32 v81, v82, v83
	v_cvt_pk_bf16_f32 v82, v88, v89
	v_cvt_pk_bf16_f32 v83, v86, v87
	s_and_b64 vcc, exec, s[12:13]
	s_mov_b64 s[2:3], -1
	global_store_dwordx4 v[78:79], v[80:83], off nt
	s_cbranch_vccnz .LBB0_446
	s_and_b64 vcc, exec, s[8:9]
	v_mov_b32_e32 v81, v73
	v_mov_b32_e32 v80, v72
	v_mov_b32_e32 v83, v71
	v_mov_b32_e32 v82, v70
	v_mov_b32_e32 v85, v69
	v_mov_b32_e32 v84, v68
	v_mov_b32_e32 v87, v67
	v_mov_b32_e32 v86, v66
	s_cbranch_vccnz .LBB0_432
	v_pk_mul_f32 v[80:81], v[70:71], s[60:61] op_sel_hi:[1,0]
	v_pk_mul_f32 v[82:83], v[72:73], s[60:61] op_sel_hi:[1,0]
	v_exp_f32_e32 v80, v80
	v_exp_f32_e32 v81, v81
	v_exp_f32_e32 v84, v82
	v_exp_f32_e32 v85, v83
	v_pk_mul_f32 v[86:87], v[68:69], s[60:61] op_sel_hi:[1,0]
	v_pk_add_f32 v[80:81], v[80:81], 1.0 op_sel_hi:[1,0]
	v_exp_f32_e32 v88, v86
	v_rcp_f32_e32 v82, v80
	v_rcp_f32_e32 v83, v81
	v_pk_add_f32 v[80:81], v[84:85], 1.0 op_sel_hi:[1,0]
	v_pk_mul_f32 v[84:85], v[66:67], s[60:61] op_sel_hi:[1,0]
	v_exp_f32_e32 v89, v87
	v_exp_f32_e32 v84, v84
	v_exp_f32_e32 v85, v85
	v_rcp_f32_e32 v80, v80
	v_rcp_f32_e32 v81, v81
	v_pk_add_f32 v[84:85], v[84:85], 1.0 op_sel_hi:[1,0]
	s_nop 0
	v_rcp_f32_e32 v86, v84
	v_rcp_f32_e32 v87, v85
	v_pk_add_f32 v[84:85], v[88:89], 1.0 op_sel_hi:[1,0]
	s_nop 0
	v_rcp_f32_e32 v84, v84
	v_rcp_f32_e32 v85, v85

; __device__ __forceinline__ unsigned cvt_pk_bf16(float lo, float hi) { unsigned r; asm volatile("v_cvt_pk_bf16_f32 %0, %1, %2" : "=v"(r) : "v"(lo), "v"(hi)); return r; }
;     __device__ __forceinline__ void operator()(const f32x4 (&acc)[2][2][4][2], const Unit& u, int wr, int wc, int fr, int fq) const {
;     ...
;                     u32x4 w; w.x = cvt_pk_bf16(v0[0], v0[1]); w.y = cvt_pk_bf16(v0[2], v0[3]); w.z = cvt_pk_bf16(v1[0], v1[1]); w.w = cvt_pk_bf16(v1[2], v1[3]);
;                     *(u32x4*)(rowp + bj * HALF) = w; }
;                 if (st) { s += __shfl_xor(s, 16); s += __shfl_xor(s, 32); q += __shfl_xor(q, 16); q += __shfl_xor(q, 32);
;                     if (fq == 0) { unsafeAtomicAdd(vsum + row, s); unsafeAtomicAdd(vsq + row, q); } } }
.LBB0_435:
	s_and_b64 vcc, exec, s[10:11]
	v_cvt_pk_bf16_f32 v66, v82, v83
	v_cvt_pk_bf16_f32 v67, v80, v81
	v_cvt_pk_bf16_f32 v68, v86, v87
	v_cvt_pk_bf16_f32 v69, v84, v85
	global_store_dwordx4 v[78:79], v[66:69], off offset:256 nt
	s_cbranch_vccnz .LBB0_439
	s_nop 0
	v_and_b32_e32 v67, 64, v153
	v_xor_b32_e32 v66, 16, v153
	v_add_u32_e32 v67, 64, v67
	v_cmp_lt_i32_e32 vcc, v66, v67
	v_xor_b32_e32 v69, 32, v153
	s_nop 0
	v_cndmask_b32_e32 v66, v153, v66, vcc
	v_lshlrev_b32_e32 v66, 2, v66
	ds_bpermute_b32 v68, v66, v77
	ds_bpermute_b32 v70, v66, v76
	v_cmp_lt_i32_e32 vcc, v69, v67
	s_waitcnt lgkmcnt(0)
	v_add_f32_e32 v66, v77, v68
	v_cndmask_b32_e32 v67, v153, v69, vcc
	v_lshlrev_b32_e32 v69, 2, v67
	v_add_f32_e32 v68, v76, v70
	ds_bpermute_b32 v67, v69, v66
	ds_bpermute_b32 v69, v69, v68
	s_and_saveexec_b64 s[2:3], s[4:5]
	s_cbranch_execz .LBB0_438
	v_lshlrev_b64 v[70:71], 2, v[74:75]
	v_lshl_add_u64 v[72:73], s[56:57], 0, v[70:71]
	v_lshl_add_u64 v[70:71], s[54:55], 0, v[70:71]
	s_waitcnt lgkmcnt(0)
	v_add_f32_e32 v66, v66, v67
	v_add_f32_e32 v67, v68, v69
	global_atomic_add_f32 v[70:71], v66, off
	global_atomic_add_f32 v[72:73], v67, off

; __device__ __forceinline__ unsigned cvt_pk_bf16(float lo, float hi) { unsigned r; asm volatile("v_cvt_pk_bf16_f32 %0, %1, %2" : "=v"(r) : "v"(lo), "v"(hi)); return r; }
; __device__ __forceinline__ f32x2p gelu_tanh_pk(f32x2p v) { const f32x2p t = v * (v * v * -0.10294324f + -2.3022082f); return v * rcp1p_exp2_pk(t); }
; __device__ __forceinline__ f32x2p sigmoid_pk(f32x2p z) { return rcp1p_exp2_pk(z * -1.4426950409f); }
;     __device__ __forceinline__ void operator()(const f32x4 (&acc)[2][2][4][2], const Unit& u, int wr, int wc, int fr, int fq) const {
;     ...
;             for (int m = 0; m < 4; ++m) { const int row = row0 + ai * HALF + m * 16; bf16_t* rowp = base + (size_t)row * ldc + col0; float s = 0.f, q = 0.f;
; #pragma unroll
;                 for (int bj = 0; bj < 2; ++bj) { f32x4 v0 = acc[ai][bj][m][0], v1 = acc[ai][bj][m][1];
;                     if (act == 1) { const f32x2p a0 = gelu_tanh_pk((f32x2p){v0[0], v0[1]}), a1 = gelu_tanh_pk((f32x2p){v0[2], v0[3]}), a2 = gelu_tanh_pk((f32x2p){v1[0], v1[1]}), a3 = gelu_tanh_pk((f32x2p){v1[2], v1[3]});
;                         v0 = (f32x4){a0.x, a0.y, a1.x, a1.y}; v1 = (f32x4){a2.x, a2.y, a3.x, a3.y}; }
;                     else if (act == 2) { const f32x2p a0 = sigmoid_pk((f32x2p){v0[0], v0[1]}), a1 = sigmoid_pk((f32x2p){v0[2], v0[3]}), a2 = sigmoid_pk((f32x2p){v1[0], v1[1]}), a3 = sigmoid_pk((f32x2p){v1[2], v1[3]});
;                         v0 = (f32x4){a0.x, a0.y, a1.x, a1.y}; v1 = (f32x4){a2.x, a2.y, a3.x, a3.y}; }
;                     if (st) {
; #pragma unroll
;                         for (int j = 0; j < 4; ++j) { s += v0[j] + v1[j]; q += v0[j] * v0[j] + v1[j] * v1[j]; } }
;                     u32x4 w; w.x = cvt_pk_bf16(v0[0], v0[1]); w.y = cvt_pk_bf16(v0[2], v0[3]); w.z = cvt_pk_bf16(v1[0], v1[1]); w.w = cvt_pk_bf16(v1[2], v1[3]);
;                     *(u32x4*)(rowp + bj * HALF) = w; }
.LBB0_452:
	v_add_u32_e32 v58, 0x80, v124
	v_ashrrev_i32_e32 v59, 31, v58
	v_mul_lo_u32 v64, s86, v59
	v_mul_lo_u32 v65, s87, v58
	v_mad_u64_u32 v[62:63], s[2:3], s86, v58, 0
	v_add3_u32 v63, v63, v64, v65
	v_lshl_add_u64 v[62:63], v[62:63], 1, v[122:123]
	s_waitcnt lgkmcnt(0)
	v_cvt_pk_bf16_f32 v64, v68, v69
	v_cvt_pk_bf16_f32 v65, v66, v67
	v_cvt_pk_bf16_f32 v66, v72, v73
	v_cvt_pk_bf16_f32 v67, v70, v71
	s_and_b64 vcc, exec, s[12:13]
	s_mov_b64 s[2:3], -1
	global_store_dwordx4 v[62:63], v[64:67], off nt
	s_cbranch_vccnz .LBB0_469
	s_and_b64 vcc, exec, s[8:9]
	v_mov_b32_e32 v65, v57
	v_mov_b32_e32 v64, v56
	v_mov_b32_e32 v67, v55
	v_mov_b32_e32 v66, v54
	v_mov_b32_e32 v69, v53
	v_mov_b32_e32 v68, v52
	v_mov_b32_e32 v71, v51
	v_mov_b32_e32 v70, v50
	s_cbranch_vccnz .LBB0_455
	v_pk_mul_f32 v[64:65], v[54:55], s[60:61] op_sel_hi:[1,0]
	v_pk_mul_f32 v[66:67], v[56:57], s[60:61] op_sel_hi:[1,0]
	v_exp_f32_e32 v64, v64
	v_exp_f32_e32 v65, v65
	v_exp_f32_e32 v68, v66
	v_exp_f32_e32 v69, v67
	v_pk_mul_f32 v[70:71], v[52:53], s[60:61] op_sel_hi:[1,0]
	v_pk_add_f32 v[64:65], v[64:65], 1.0 op_sel_hi:[1,0]
	v_exp_f32_e32 v72, v70
	v_rcp_f32_e32 v66, v64
	v_rcp_f32_e32 v67, v65
	v_pk_add_f32 v[64:65], v[68:69], 1.0 op_sel_hi:[1,0]
	v_pk_mul_f32 v[68:69], v[50:51], s[60:61] op_sel_hi:[1,0]
	v_exp_f32_e32 v73, v71
	v_exp_f32_e32 v68, v68
	v_exp_f32_e32 v69, v69
	v_rcp_f32_e32 v64, v64
	v_rcp_f32_e32 v65, v65
	v_pk_add_f32 v[68:69], v[68:69], 1.0 op_sel_hi:[1,0]
	s_nop 0
	v_rcp_f32_e32 v70, v68
	v_rcp_f32_e32 v71, v69
	v_pk_add_f32 v[68:69], v[72:73], 1.0 op_sel_hi:[1,0]
	s_nop 0
	v_rcp_f32_e32 v68, v68
	v_rcp_f32_e32 v69, v69

; __device__ __forceinline__ unsigned cvt_pk_bf16(float lo, float hi) { unsigned r; asm volatile("v_cvt_pk_bf16_f32 %0, %1, %2" : "=v"(r) : "v"(lo), "v"(hi)); return r; }
;     __device__ __forceinline__ void operator()(const f32x4 (&acc)[2][2][4][2], const Unit& u, int wr, int wc, int fr, int fq) const {
;     ...
;                     u32x4 w; w.x = cvt_pk_bf16(v0[0], v0[1]); w.y = cvt_pk_bf16(v0[2], v0[3]); w.z = cvt_pk_bf16(v1[0], v1[1]); w.w = cvt_pk_bf16(v1[2], v1[3]);
;                     *(u32x4*)(rowp + bj * HALF) = w; }
;                 if (st) { s += __shfl_xor(s, 16); s += __shfl_xor(s, 32); q += __shfl_xor(q, 16); q += __shfl_xor(q, 32);
;                     if (fq == 0) { unsafeAtomicAdd(vsum + row, s); unsafeAtomicAdd(vsq + row, q); } } }
.LBB0_458:
	s_and_b64 vcc, exec, s[10:11]
	v_cvt_pk_bf16_f32 v50, v66, v67
	v_cvt_pk_bf16_f32 v51, v64, v65
	v_cvt_pk_bf16_f32 v52, v70, v71
	v_cvt_pk_bf16_f32 v53, v68, v69
	global_store_dwordx4 v[62:63], v[50:53], off offset:256 nt
	s_cbranch_vccnz .LBB0_462
	s_nop 0
	v_and_b32_e32 v51, 64, v153
	v_xor_b32_e32 v50, 16, v153
	v_add_u32_e32 v51, 64, v51
	v_cmp_lt_i32_e32 vcc, v50, v51
	v_xor_b32_e32 v53, 32, v153
	s_nop 0
	v_cndmask_b32_e32 v50, v153, v50, vcc
	v_lshlrev_b32_e32 v50, 2, v50
	ds_bpermute_b32 v52, v50, v61
	ds_bpermute_b32 v54, v50, v60
	v_cmp_lt_i32_e32 vcc, v53, v51
	s_waitcnt lgkmcnt(0)
	v_add_f32_e32 v50, v61, v52
	v_cndmask_b32_e32 v51, v153, v53, vcc
	v_lshlrev_b32_e32 v53, 2, v51
	v_add_f32_e32 v52, v60, v54
	ds_bpermute_b32 v51, v53, v50
	ds_bpermute_b32 v53, v53, v52
	s_and_saveexec_b64 s[2:3], s[4:5]
	s_cbranch_execz .LBB0_461
	v_lshlrev_b64 v[54:55], 2, v[58:59]
	v_lshl_add_u64 v[56:57], s[56:57], 0, v[54:55]
	v_lshl_add_u64 v[54:55], s[54:55], 0, v[54:55]
	s_waitcnt lgkmcnt(0)
	v_add_f32_e32 v50, v50, v51
	v_add_f32_e32 v51, v52, v53
	global_atomic_add_f32 v[54:55], v50, off
	global_atomic_add_f32 v[56:57], v51, off

; __device__ __forceinline__ unsigned cvt_pk_bf16(float lo, float hi) { unsigned r; asm volatile("v_cvt_pk_bf16_f32 %0, %1, %2" : "=v"(r) : "v"(lo), "v"(hi)); return r; }
; __device__ __forceinline__ f32x2p gelu_tanh_pk(f32x2p v) { const f32x2p t = v * (v * v * -0.10294324f + -2.3022082f); return v * rcp1p_exp2_pk(t); }
; __device__ __forceinline__ f32x2p sigmoid_pk(f32x2p z) { return rcp1p_exp2_pk(z * -1.4426950409f); }
;     __device__ __forceinline__ void operator()(const f32x4 (&acc)[2][2][4][2], const Unit& u, int wr, int wc, int fr, int fq) const {
;     ...
;             for (int m = 0; m < 4; ++m) { const int row = row0 + ai * HALF + m * 16; bf16_t* rowp = base + (size_t)row * ldc + col0; float s = 0.f, q = 0.f;
; #pragma unroll
;                 for (int bj = 0; bj < 2; ++bj) { f32x4 v0 = acc[ai][bj][m][0], v1 = acc[ai][bj][m][1];
;                     if (act == 1) { const f32x2p a0 = gelu_tanh_pk((f32x2p){v0[0], v0[1]}), a1 = gelu_tanh_pk((f32x2p){v0[2], v0[3]}), a2 = gelu_tanh_pk((f32x2p){v1[0], v1[1]}), a3 = gelu_tanh_pk((f32x2p){v1[2], v1[3]});
;                         v0 = (f32x4){a0.x, a0.y, a1.x, a1.y}; v1 = (f32x4){a2.x, a2.y, a3.x, a3.y}; }
;                     else if (act == 2) { const f32x2p a0 = sigmoid_pk((f32x2p){v0[0], v0[1]}), a1 = sigmoid_pk((f32x2p){v0[2], v0[3]}), a2 = sigmoid_pk((f32x2p){v1[0], v1[1]}), a3 = sigmoid_pk((f32x2p){v1[2], v1[3]});
;                         v0 = (f32x4){a0.x, a0.y, a1.x, a1.y}; v1 = (f32x4){a2.x, a2.y, a3.x, a3.y}; }
;                     if (st) {
; #pragma unroll
;                         for (int j = 0; j < 4; ++j) { s += v0[j] + v1[j]; q += v0[j] * v0[j] + v1[j] * v1[j]; } }
;                     u32x4 w; w.x = cvt_pk_bf16(v0[0], v0[1]); w.y = cvt_pk_bf16(v0[2], v0[3]); w.z = cvt_pk_bf16(v1[0], v1[1]); w.w = cvt_pk_bf16(v1[2], v1[3]);
;                     *(u32x4*)(rowp + bj * HALF) = w; }
.LBB0_475:
	v_add_u32_e32 v42, 0x90, v124
	v_ashrrev_i32_e32 v43, 31, v42
	v_mul_lo_u32 v48, s86, v43
	v_mul_lo_u32 v49, s87, v42
	v_mad_u64_u32 v[46:47], s[2:3], s86, v42, 0
	v_add3_u32 v47, v47, v48, v49
	v_lshl_add_u64 v[46:47], v[46:47], 1, v[122:123]
	s_waitcnt lgkmcnt(0)
	v_cvt_pk_bf16_f32 v48, v52, v53
	v_cvt_pk_bf16_f32 v49, v50, v51
	v_cvt_pk_bf16_f32 v50, v56, v57
	v_cvt_pk_bf16_f32 v51, v54, v55
	s_and_b64 vcc, exec, s[12:13]
	s_mov_b64 s[2:3], -1
	global_store_dwordx4 v[46:47], v[48:51], off nt
	s_cbranch_vccnz .LBB0_492
	s_and_b64 vcc, exec, s[8:9]
	v_mov_b32_e32 v49, v41
	v_mov_b32_e32 v48, v40
	v_mov_b32_e32 v51, v39
	v_mov_b32_e32 v50, v38
	v_mov_b32_e32 v53, v37
	v_mov_b32_e32 v52, v36
	v_mov_b32_e32 v55, v35
	v_mov_b32_e32 v54, v34
	s_cbranch_vccnz .LBB0_478
	v_pk_mul_f32 v[48:49], v[38:39], s[60:61] op_sel_hi:[1,0]
	v_pk_mul_f32 v[50:51], v[40:41], s[60:61] op_sel_hi:[1,0]
	v_exp_f32_e32 v48, v48
	v_exp_f32_e32 v49, v49
	v_exp_f32_e32 v52, v50
	v_exp_f32_e32 v53, v51
	v_pk_mul_f32 v[54:55], v[36:37], s[60:61] op_sel_hi:[1,0]
	v_pk_add_f32 v[48:49], v[48:49], 1.0 op_sel_hi:[1,0]
	v_exp_f32_e32 v56, v54
	v_rcp_f32_e32 v50, v48
	v_rcp_f32_e32 v51, v49
	v_pk_add_f32 v[48:49], v[52:53], 1.0 op_sel_hi:[1,0]
	v_pk_mul_f32 v[52:53], v[34:35], s[60:61] op_sel_hi:[1,0]
	v_exp_f32_e32 v57, v55
	v_exp_f32_e32 v52, v52
	v_exp_f32_e32 v53, v53
	v_rcp_f32_e32 v48, v48
	v_rcp_f32_e32 v49, v49
	v_pk_add_f32 v[52:53], v[52:53], 1.0 op_sel_hi:[1,0]
	s_nop 0
	v_rcp_f32_e32 v54, v52
	v_rcp_f32_e32 v55, v53
	v_pk_add_f32 v[52:53], v[56:57], 1.0 op_sel_hi:[1,0]
	s_nop 0
	v_rcp_f32_e32 v52, v52
	v_rcp_f32_e32 v53, v53

; __device__ __forceinline__ unsigned cvt_pk_bf16(float lo, float hi) { unsigned r; asm volatile("v_cvt_pk_bf16_f32 %0, %1, %2" : "=v"(r) : "v"(lo), "v"(hi)); return r; }
;     __device__ __forceinline__ void operator()(const f32x4 (&acc)[2][2][4][2], const Unit& u, int wr, int wc, int fr, int fq) const {
;     ...
;                     u32x4 w; w.x = cvt_pk_bf16(v0[0], v0[1]); w.y = cvt_pk_bf16(v0[2], v0[3]); w.z = cvt_pk_bf16(v1[0], v1[1]); w.w = cvt_pk_bf16(v1[2], v1[3]);
;                     *(u32x4*)(rowp + bj * HALF) = w; }
;                 if (st) { s += __shfl_xor(s, 16); s += __shfl_xor(s, 32); q += __shfl_xor(q, 16); q += __shfl_xor(q, 32);
;                     if (fq == 0) { unsafeAtomicAdd(vsum + row, s); unsafeAtomicAdd(vsq + row, q); } } }
.LBB0_481:
	s_and_b64 vcc, exec, s[10:11]
	v_cvt_pk_bf16_f32 v34, v50, v51
	v_cvt_pk_bf16_f32 v35, v48, v49
	v_cvt_pk_bf16_f32 v36, v54, v55
	v_cvt_pk_bf16_f32 v37, v52, v53
	global_store_dwordx4 v[46:47], v[34:37], off offset:256 nt
	s_cbranch_vccnz .LBB0_485
	s_nop 0
	v_and_b32_e32 v35, 64, v153
	v_xor_b32_e32 v34, 16, v153
	v_add_u32_e32 v35, 64, v35
	v_cmp_lt_i32_e32 vcc, v34, v35
	v_xor_b32_e32 v37, 32, v153
	s_nop 0
	v_cndmask_b32_e32 v34, v153, v34, vcc
	v_lshlrev_b32_e32 v34, 2, v34
	ds_bpermute_b32 v36, v34, v45
	ds_bpermute_b32 v38, v34, v44
	v_cmp_lt_i32_e32 vcc, v37, v35
	s_waitcnt lgkmcnt(0)
	v_add_f32_e32 v34, v45, v36
	v_cndmask_b32_e32 v35, v153, v37, vcc
	v_lshlrev_b32_e32 v37, 2, v35
	v_add_f32_e32 v36, v44, v38
	ds_bpermute_b32 v35, v37, v34
	ds_bpermute_b32 v37, v37, v36
	s_and_saveexec_b64 s[2:3], s[4:5]
	s_cbranch_execz .LBB0_484
	v_lshlrev_b64 v[38:39], 2, v[42:43]
	v_lshl_add_u64 v[40:41], s[56:57], 0, v[38:39]
	v_lshl_add_u64 v[38:39], s[54:55], 0, v[38:39]
	s_waitcnt lgkmcnt(0)
	v_add_f32_e32 v34, v34, v35
	v_add_f32_e32 v35, v36, v37
	global_atomic_add_f32 v[38:39], v34, off
	global_atomic_add_f32 v[40:41], v35, off

; __device__ __forceinline__ unsigned cvt_pk_bf16(float lo, float hi) { unsigned r; asm volatile("v_cvt_pk_bf16_f32 %0, %1, %2" : "=v"(r) : "v"(lo), "v"(hi)); return r; }
; __device__ __forceinline__ f32x2p gelu_tanh_pk(f32x2p v) { const f32x2p t = v * (v * v * -0.10294324f + -2.3022082f); return v * rcp1p_exp2_pk(t); }
; __device__ __forceinline__ f32x2p sigmoid_pk(f32x2p z) { return rcp1p_exp2_pk(z * -1.4426950409f); }
;     __device__ __forceinline__ void operator()(const f32x4 (&acc)[2][2][4][2], const Unit& u, int wr, int wc, int fr, int fq) const {
;     ...
;             for (int m = 0; m < 4; ++m) { const int row = row0 + ai * HALF + m * 16; bf16_t* rowp = base + (size_t)row * ldc + col0; float s = 0.f, q = 0.f;
; #pragma unroll
;                 for (int bj = 0; bj < 2; ++bj) { f32x4 v0 = acc[ai][bj][m][0], v1 = acc[ai][bj][m][1];
;                     if (act == 1) { const f32x2p a0 = gelu_tanh_pk((f32x2p){v0[0], v0[1]}), a1 = gelu_tanh_pk((f32x2p){v0[2], v0[3]}), a2 = gelu_tanh_pk((f32x2p){v1[0], v1[1]}), a3 = gelu_tanh_pk((f32x2p){v1[2], v1[3]});
;                         v0 = (f32x4){a0.x, a0.y, a1.x, a1.y}; v1 = (f32x4){a2.x, a2.y, a3.x, a3.y}; }
;                     else if (act == 2) { const f32x2p a0 = sigmoid_pk((f32x2p){v0[0], v0[1]}), a1 = sigmoid_pk((f32x2p){v0[2], v0[3]}), a2 = sigmoid_pk((f32x2p){v1[0], v1[1]}), a3 = sigmoid_pk((f32x2p){v1[2], v1[3]});
;                         v0 = (f32x4){a0.x, a0.y, a1.x, a1.y}; v1 = (f32x4){a2.x, a2.y, a3.x, a3.y}; }
;                     if (st) {
; #pragma unroll
;                         for (int j = 0; j < 4; ++j) { s += v0[j] + v1[j]; q += v0[j] * v0[j] + v1[j] * v1[j]; } }
;                     u32x4 w; w.x = cvt_pk_bf16(v0[0], v0[1]); w.y = cvt_pk_bf16(v0[2], v0[3]); w.z = cvt_pk_bf16(v1[0], v1[1]); w.w = cvt_pk_bf16(v1[2], v1[3]);
;                     *(u32x4*)(rowp + bj * HALF) = w; }
.LBB0_498:
	v_add_u32_e32 v26, 0xa0, v124
	v_ashrrev_i32_e32 v27, 31, v26
	v_mul_lo_u32 v32, s86, v27
	v_mul_lo_u32 v33, s87, v26
	v_mad_u64_u32 v[30:31], s[2:3], s86, v26, 0
	v_add3_u32 v31, v31, v32, v33
	v_lshl_add_u64 v[30:31], v[30:31], 1, v[122:123]
	s_waitcnt lgkmcnt(0)
	v_cvt_pk_bf16_f32 v32, v36, v37
	v_cvt_pk_bf16_f32 v33, v34, v35
	v_cvt_pk_bf16_f32 v34, v40, v41
	v_cvt_pk_bf16_f32 v35, v38, v39
	s_and_b64 vcc, exec, s[12:13]
	s_mov_b64 s[2:3], -1
	global_store_dwordx4 v[30:31], v[32:35], off nt
	s_cbranch_vccnz .LBB0_515
	s_and_b64 vcc, exec, s[8:9]
	v_mov_b32_e32 v33, v25
	v_mov_b32_e32 v32, v24
	v_mov_b32_e32 v35, v23
	v_mov_b32_e32 v34, v22
	v_mov_b32_e32 v37, v21
	v_mov_b32_e32 v36, v20
	v_mov_b32_e32 v39, v19
	v_mov_b32_e32 v38, v18
	s_cbranch_vccnz .LBB0_501
	v_pk_mul_f32 v[32:33], v[22:23], s[60:61] op_sel_hi:[1,0]
	v_pk_mul_f32 v[34:35], v[24:25], s[60:61] op_sel_hi:[1,0]
	v_exp_f32_e32 v32, v32
	v_exp_f32_e32 v33, v33
	v_exp_f32_e32 v36, v34
	v_exp_f32_e32 v37, v35
	v_pk_mul_f32 v[38:39], v[20:21], s[60:61] op_sel_hi:[1,0]
	v_pk_add_f32 v[32:33], v[32:33], 1.0 op_sel_hi:[1,0]
	v_exp_f32_e32 v40, v38
	v_rcp_f32_e32 v34, v32
	v_rcp_f32_e32 v35, v33
	v_pk_add_f32 v[32:33], v[36:37], 1.0 op_sel_hi:[1,0]
	v_pk_mul_f32 v[36:37], v[18:19], s[60:61] op_sel_hi:[1,0]
	v_exp_f32_e32 v41, v39
	v_exp_f32_e32 v36, v36
	v_exp_f32_e32 v37, v37
	v_rcp_f32_e32 v32, v32
	v_rcp_f32_e32 v33, v33
	v_pk_add_f32 v[36:37], v[36:37], 1.0 op_sel_hi:[1,0]
	s_nop 0
	v_rcp_f32_e32 v38, v36
	v_rcp_f32_e32 v39, v37
	v_pk_add_f32 v[36:37], v[40:41], 1.0 op_sel_hi:[1,0]
	s_nop 0
	v_rcp_f32_e32 v36, v36
	v_rcp_f32_e32 v37, v37

; __device__ __forceinline__ unsigned cvt_pk_bf16(float lo, float hi) { unsigned r; asm volatile("v_cvt_pk_bf16_f32 %0, %1, %2" : "=v"(r) : "v"(lo), "v"(hi)); return r; }
;     __device__ __forceinline__ void operator()(const f32x4 (&acc)[2][2][4][2], const Unit& u, int wr, int wc, int fr, int fq) const {
;     ...
;                     u32x4 w; w.x = cvt_pk_bf16(v0[0], v0[1]); w.y = cvt_pk_bf16(v0[2], v0[3]); w.z = cvt_pk_bf16(v1[0], v1[1]); w.w = cvt_pk_bf16(v1[2], v1[3]);
;                     *(u32x4*)(rowp + bj * HALF) = w; }
;                 if (st) { s += __shfl_xor(s, 16); s += __shfl_xor(s, 32); q += __shfl_xor(q, 16); q += __shfl_xor(q, 32);
;                     if (fq == 0) { unsafeAtomicAdd(vsum + row, s); unsafeAtomicAdd(vsq + row, q); } } }
.LBB0_504:
	s_and_b64 vcc, exec, s[10:11]
	v_cvt_pk_bf16_f32 v18, v34, v35
	v_cvt_pk_bf16_f32 v19, v32, v33
	v_cvt_pk_bf16_f32 v20, v38, v39
	v_cvt_pk_bf16_f32 v21, v36, v37
	global_store_dwordx4 v[30:31], v[18:21], off offset:256 nt
	s_cbranch_vccnz .LBB0_508
	s_nop 0
	v_and_b32_e32 v19, 64, v153
	v_xor_b32_e32 v18, 16, v153
	v_add_u32_e32 v19, 64, v19
	v_cmp_lt_i32_e32 vcc, v18, v19
	v_xor_b32_e32 v21, 32, v153
	s_nop 0
	v_cndmask_b32_e32 v18, v153, v18, vcc
	v_lshlrev_b32_e32 v18, 2, v18
	ds_bpermute_b32 v20, v18, v29
	ds_bpermute_b32 v22, v18, v28
	v_cmp_lt_i32_e32 vcc, v21, v19
	s_waitcnt lgkmcnt(0)
	v_add_f32_e32 v18, v29, v20
	v_cndmask_b32_e32 v19, v153, v21, vcc
	v_lshlrev_b32_e32 v21, 2, v19
	v_add_f32_e32 v20, v28, v22
	ds_bpermute_b32 v19, v21, v18
	ds_bpermute_b32 v21, v21, v20
	s_and_saveexec_b64 s[2:3], s[4:5]
	s_cbranch_execz .LBB0_507
	v_lshlrev_b64 v[22:23], 2, v[26:27]
	v_lshl_add_u64 v[24:25], s[56:57], 0, v[22:23]
	v_lshl_add_u64 v[22:23], s[54:55], 0, v[22:23]
	s_waitcnt lgkmcnt(0)
	v_add_f32_e32 v18, v18, v19
	v_add_f32_e32 v19, v20, v21
	global_atomic_add_f32 v[22:23], v18, off
	global_atomic_add_f32 v[24:25], v19, off

; __device__ __forceinline__ unsigned cvt_pk_bf16(float lo, float hi) { unsigned r; asm volatile("v_cvt_pk_bf16_f32 %0, %1, %2" : "=v"(r) : "v"(lo), "v"(hi)); return r; }
; __device__ __forceinline__ f32x2p gelu_tanh_pk(f32x2p v) { const f32x2p t = v * (v * v * -0.10294324f + -2.3022082f); return v * rcp1p_exp2_pk(t); }
; __device__ __forceinline__ f32x2p sigmoid_pk(f32x2p z) { return rcp1p_exp2_pk(z * -1.4426950409f); }
;     __device__ __forceinline__ void operator()(const f32x4 (&acc)[2][2][4][2], const Unit& u, int wr, int wc, int fr, int fq) const {
;     ...
;             for (int m = 0; m < 4; ++m) { const int row = row0 + ai * HALF + m * 16; bf16_t* rowp = base + (size_t)row * ldc + col0; float s = 0.f, q = 0.f;
; #pragma unroll
;                 for (int bj = 0; bj < 2; ++bj) { f32x4 v0 = acc[ai][bj][m][0], v1 = acc[ai][bj][m][1];
;                     if (act == 1) { const f32x2p a0 = gelu_tanh_pk((f32x2p){v0[0], v0[1]}), a1 = gelu_tanh_pk((f32x2p){v0[2], v0[3]}), a2 = gelu_tanh_pk((f32x2p){v1[0], v1[1]}), a3 = gelu_tanh_pk((f32x2p){v1[2], v1[3]});
;                         v0 = (f32x4){a0.x, a0.y, a1.x, a1.y}; v1 = (f32x4){a2.x, a2.y, a3.x, a3.y}; }
;                     else if (act == 2) { const f32x2p a0 = sigmoid_pk((f32x2p){v0[0], v0[1]}), a1 = sigmoid_pk((f32x2p){v0[2], v0[3]}), a2 = sigmoid_pk((f32x2p){v1[0], v1[1]}), a3 = sigmoid_pk((f32x2p){v1[2], v1[3]});
;                         v0 = (f32x4){a0.x, a0.y, a1.x, a1.y}; v1 = (f32x4){a2.x, a2.y, a3.x, a3.y}; }
;                     if (st) {
; #pragma unroll
;                         for (int j = 0; j < 4; ++j) { s += v0[j] + v1[j]; q += v0[j] * v0[j] + v1[j] * v1[j]; } }
;                     u32x4 w; w.x = cvt_pk_bf16(v0[0], v0[1]); w.y = cvt_pk_bf16(v0[2], v0[3]); w.z = cvt_pk_bf16(v1[0], v1[1]); w.w = cvt_pk_bf16(v1[2], v1[3]);
;                     *(u32x4*)(rowp + bj * HALF) = w; }
.LBB0_521:
	v_add_u32_e32 v10, 0xb0, v124
	v_ashrrev_i32_e32 v11, 31, v10
	v_mul_lo_u32 v16, s86, v11
	v_mul_lo_u32 v17, s87, v10
	v_mad_u64_u32 v[14:15], s[2:3], s86, v10, 0
	v_add3_u32 v15, v15, v16, v17
	v_lshl_add_u64 v[14:15], v[14:15], 1, v[122:123]
	s_waitcnt lgkmcnt(0)
	v_cvt_pk_bf16_f32 v16, v20, v21
	v_cvt_pk_bf16_f32 v17, v18, v19
	v_cvt_pk_bf16_f32 v18, v24, v25
	v_cvt_pk_bf16_f32 v19, v22, v23
	s_and_b64 vcc, exec, s[12:13]
	s_mov_b64 s[2:3], -1
	global_store_dwordx4 v[14:15], v[16:19], off nt
	s_cbranch_vccnz .LBB0_534
	s_and_b64 vcc, exec, s[8:9]
	v_mov_b32_e32 v17, v9
	v_mov_b32_e32 v16, v8
	v_mov_b32_e32 v19, v7
	v_mov_b32_e32 v18, v6
	v_mov_b32_e32 v21, v5
	v_mov_b32_e32 v20, v4
	v_mov_b32_e32 v23, v3
	v_mov_b32_e32 v22, v2
	s_cbranch_vccnz .LBB0_524
	v_pk_mul_f32 v[16:17], v[6:7], s[60:61] op_sel_hi:[1,0]
	v_pk_mul_f32 v[18:19], v[8:9], s[60:61] op_sel_hi:[1,0]
	v_exp_f32_e32 v16, v16
	v_exp_f32_e32 v17, v17
	v_exp_f32_e32 v20, v18
	v_exp_f32_e32 v21, v19
	v_pk_mul_f32 v[22:23], v[4:5], s[60:61] op_sel_hi:[1,0]
	v_pk_add_f32 v[16:17], v[16:17], 1.0 op_sel_hi:[1,0]
	v_exp_f32_e32 v24, v22
	v_rcp_f32_e32 v18, v16
	v_rcp_f32_e32 v19, v17
	v_pk_add_f32 v[16:17], v[20:21], 1.0 op_sel_hi:[1,0]
	v_pk_mul_f32 v[20:21], v[2:3], s[60:61] op_sel_hi:[1,0]
	v_exp_f32_e32 v25, v23
	v_exp_f32_e32 v20, v20
	v_exp_f32_e32 v21, v21
	v_rcp_f32_e32 v16, v16
	v_rcp_f32_e32 v17, v17
	v_pk_add_f32 v[20:21], v[20:21], 1.0 op_sel_hi:[1,0]
	s_nop 0
	v_rcp_f32_e32 v22, v20
	v_rcp_f32_e32 v23, v21
	v_pk_add_f32 v[20:21], v[24:25], 1.0 op_sel_hi:[1,0]
	s_nop 0
	v_rcp_f32_e32 v20, v20
	v_rcp_f32_e32 v21, v21

; __device__ __forceinline__ unsigned cvt_pk_bf16(float lo, float hi) { unsigned r; asm volatile("v_cvt_pk_bf16_f32 %0, %1, %2" : "=v"(r) : "v"(lo), "v"(hi)); return r; }
;     __device__ __forceinline__ void operator()(const f32x4 (&acc)[2][2][4][2], const Unit& u, int wr, int wc, int fr, int fq) const {
;     ...
;                     u32x4 w; w.x = cvt_pk_bf16(v0[0], v0[1]); w.y = cvt_pk_bf16(v0[2], v0[3]); w.z = cvt_pk_bf16(v1[0], v1[1]); w.w = cvt_pk_bf16(v1[2], v1[3]);
;                     *(u32x4*)(rowp + bj * HALF) = w; }
;                 if (st) { s += __shfl_xor(s, 16); s += __shfl_xor(s, 32); q += __shfl_xor(q, 16); q += __shfl_xor(q, 32);
;                     if (fq == 0) { unsafeAtomicAdd(vsum + row, s); unsafeAtomicAdd(vsq + row, q); } } }
.LBB0_527:
	s_and_b64 vcc, exec, s[10:11]
	v_cvt_pk_bf16_f32 v2, v18, v19
	v_cvt_pk_bf16_f32 v3, v16, v17
	v_cvt_pk_bf16_f32 v4, v22, v23
	v_cvt_pk_bf16_f32 v5, v20, v21
	global_store_dwordx4 v[14:15], v[2:5], off offset:256 nt
	s_cbranch_vccnz .LBB0_531
	s_nop 0
	v_and_b32_e32 v3, 64, v153
	v_xor_b32_e32 v2, 16, v153
	v_add_u32_e32 v3, 64, v3
	v_cmp_lt_i32_e32 vcc, v2, v3
	v_xor_b32_e32 v5, 32, v153
	s_nop 0
	v_cndmask_b32_e32 v2, v153, v2, vcc
	v_lshlrev_b32_e32 v2, 2, v2
	ds_bpermute_b32 v4, v2, v13
	ds_bpermute_b32 v6, v2, v12
	v_cmp_lt_i32_e32 vcc, v5, v3
	s_waitcnt lgkmcnt(0)
	v_add_f32_e32 v2, v13, v4
	v_cndmask_b32_e32 v3, v153, v5, vcc
	v_lshlrev_b32_e32 v5, 2, v3
	v_add_f32_e32 v4, v12, v6
	ds_bpermute_b32 v3, v5, v2
	ds_bpermute_b32 v5, v5, v4
	s_and_saveexec_b64 s[2:3], s[4:5]
	s_cbranch_execz .LBB0_530
	v_lshlrev_b64 v[6:7], 2, v[10:11]
	v_lshl_add_u64 v[8:9], s[56:57], 0, v[6:7]
	v_lshl_add_u64 v[6:7], s[54:55], 0, v[6:7]
	s_waitcnt lgkmcnt(0)
	v_add_f32_e32 v2, v2, v3
	v_add_f32_e32 v3, v4, v5
	global_atomic_add_f32 v[6:7], v2, off
	global_atomic_add_f32 v[8:9], v3, off
